# a1 + E-wave K/V LDS staging writes moved before the last two PV MFMAs (address temps v221-v224)
# baseline (speedup 1.0000x reference)
.LBB0_633:
	s_add_i32 s22, s8, s41
	s_and_b32 s22, s22, 0x7f
	s_mulk_i32 s22, 0x3000
	v_lshl_add_u64 v[36:37], v[154:155], 0, s[22:23]
	global_load_dwordx4 v[140:143], v[36:37], off
	v_add_co_u32_e32 v36, vcc, s54, v36
	s_and_b32 s22, s9, 0xfe000
	s_nop 0
	v_addc_co_u32_e32 v37, vcc, 0, v37, vcc
	v_lshl_add_u64 v[38:39], v[152:153], 0, s[22:23]
	global_load_dwordx4 v[144:147], v[36:37], off
	global_load_dwordx4 v[136:139], v[38:39], off
	global_load_dwordx4 v[148:151], v[36:37], off offset:-4096
	global_load_dwordx4 v[132:135], v[38:39], off offset:64
	s_mov_b32 s22, s39
	s_mov_b32 s39, s59
	s_and_b32 s44, s41, 1
	s_add_i32 s41, s41, 1
	s_setprio 1
	s_waitcnt vmcnt(10) lgkmcnt(11)
	v_mfma_f32_32x32x16_bf16 v[32:47], v[32:35], v[84:87], 0
	v_add_f32_e32 v220, v163, v159
	v_add_f32_e32 v220, v204, v220
	v_add_f32_e32 v220, v173, v220
	s_waitcnt lgkmcnt(9)
	v_mfma_f32_32x32x16_bf16 v[48:63], v[128:131], v[84:87], 0
	v_add_f32_e32 v220, v205, v220
	v_add_f32_e32 v220, v190, v220
	v_add_f32_e32 v220, v206, v220
	s_waitcnt vmcnt(9)
	v_mfma_f32_32x32x16_bf16 v[32:47], v[116:119], v[80:83], v[32:47]
	v_add_f32_e32 v220, v191, v220
	v_add_f32_e32 v220, v207, v220
	v_add_f32_e32 v220, v192, v220
	s_waitcnt lgkmcnt(8)
	v_mfma_f32_32x32x16_bf16 v[48:63], v[124:127], v[80:83], v[48:63]
	v_add_f32_e32 v220, v208, v220
	v_add_f32_e32 v220, v193, v220
	v_add_f32_e32 v220, v209, v220
	s_waitcnt vmcnt(8) lgkmcnt(7)
	v_mfma_f32_32x32x16_bf16 v[32:47], v[112:115], v[76:79], v[32:47]
	v_add_f32_e32 v220, v194, v220
	v_add_f32_e32 v220, v210, v220
	v_add_f32_e32 v220, v195, v220
	s_waitcnt lgkmcnt(5)
	v_mfma_f32_32x32x16_bf16 v[48:63], v[108:111], v[76:79], v[48:63]
	v_add_f32_e32 v220, v211, v220
	v_add_f32_e32 v220, v196, v220
	v_add_f32_e32 v220, v212, v220
	s_waitcnt vmcnt(7)
	v_mfma_f32_32x32x16_bf16 v[32:47], v[100:103], v[72:75], v[32:47]
	v_add_f32_e32 v220, v197, v220
	v_add_f32_e32 v220, v213, v220
	v_add_f32_e32 v220, v198, v220
	s_waitcnt lgkmcnt(4)
	v_mfma_f32_32x32x16_bf16 v[48:63], v[104:107], v[72:75], v[48:63]
	v_add_f32_e32 v220, v214, v220
	v_add_f32_e32 v220, v199, v220
	v_add_f32_e32 v220, v215, v220
	s_waitcnt vmcnt(6) lgkmcnt(3)
	v_mfma_f32_32x32x16_bf16 v[32:47], v[92:95], v[68:71], v[32:47]
	v_add_f32_e32 v220, v200, v220
	v_add_f32_e32 v220, v216, v220
	s_waitcnt lgkmcnt(1)
	v_mfma_f32_32x32x16_bf16 v[48:63], v[120:123], v[68:71], v[48:63]
	v_add_f32_e32 v220, v201, v220
	v_add_f32_e32 v220, v217, v220
	s_waitcnt vmcnt(5)
	v_mfma_f32_32x32x16_bf16 v[32:47], v[88:91], v[64:67], v[32:47]
	v_add_f32_e32 v220, v202, v220
	v_add_f32_e32 v220, v218, v220
	s_waitcnt lgkmcnt(0)
	v_mfma_f32_32x32x16_bf16 v[48:63], v[96:99], v[64:67], v[48:63]
	v_add_f32_e32 v220, v203, v220
	v_add_f32_e32 v159, v219, v220
	s_setprio 0
	s_mul_i32 s43, s44, 0x2400
	v_add_u32_e32 v100, s43, v157
	ds_read_b128 v[88:91], v100 offset:39936
	ds_read_b128 v[96:99], v100 offset:39968
	ds_read_b128 v[92:95], v100 offset:44544
	ds_read_b128 v[164:167], v100 offset:44576
	ds_read_b128 v[174:177], v100 offset:40000
	ds_read_b128 v[178:181], v100 offset:40032
	ds_read_b128 v[182:185], v100 offset:44608
	ds_read_b128 v[186:189], v100 offset:44640
	v_exp_f32_e32 v163, v32
	v_exp_f32_e32 v173, v33
	v_exp_f32_e32 v190, v34
	v_exp_f32_e32 v191, v35
	v_exp_f32_e32 v192, v36
	v_exp_f32_e32 v193, v37
	v_exp_f32_e32 v194, v38
	v_exp_f32_e32 v195, v39
	v_cvt_pk_bf16_f32 v36, v163, v173
	v_cvt_pk_bf16_f32 v37, v190, v191
	v_cvt_pk_bf16_f32 v38, v192, v193
	v_cvt_pk_bf16_f32 v39, v194, v195
	v_exp_f32_e32 v196, v40
	v_exp_f32_e32 v197, v41
	s_waitcnt lgkmcnt(7)
	v_mfma_f32_32x32x16_bf16 v[16:31], v[88:91], v[36:39], v[16:31]
	v_exp_f32_e32 v198, v42
	v_exp_f32_e32 v199, v43
	v_exp_f32_e32 v200, v44
	v_exp_f32_e32 v201, v45
	v_exp_f32_e32 v202, v46
	v_exp_f32_e32 v203, v47
	v_exp_f32_e32 v204, v48
	s_waitcnt lgkmcnt(5)
	v_mfma_f32_32x32x16_bf16 v[0:15], v[92:95], v[36:39], v[0:15]
	v_exp_f32_e32 v205, v49
	s_mul_i32 s43, s22, 0x3400
	v_add_u32_e32 v40, s43, v158
	v_cvt_pk_bf16_f32 v36, v196, v197
	v_cvt_pk_bf16_f32 v37, v198, v199
	v_cvt_pk_bf16_f32 v38, v200, v201
	v_cvt_pk_bf16_f32 v39, v202, v203
	v_exp_f32_e32 v206, v50
	ds_read_b128 v[32:35], v40
	ds_read_b128 v[116:119], v40 offset:32
	ds_read_b128 v[128:131], v40 offset:6656
	ds_read_b128 v[124:127], v40 offset:6688
	ds_read_b128 v[108:111], v40 offset:6720
	ds_read_b128 v[112:115], v40 offset:64
	ds_read_b128 v[100:103], v40 offset:96
	ds_read_b128 v[104:107], v40 offset:6752
	ds_read_b128 v[92:95], v40 offset:128
	ds_read_b128 v[88:91], v40 offset:160
	v_mfma_f32_32x32x16_bf16 v[16:31], v[96:99], v[36:39], v[16:31]
	ds_read_b128 v[120:123], v40 offset:6784
	ds_read_b128 v[96:99], v40 offset:6816
	v_cvt_pk_bf16_f32 v40, v204, v205
	v_exp_f32_e32 v207, v51
	s_waitcnt lgkmcnt(14)
	v_mfma_f32_32x32x16_bf16 v[0:15], v[164:167], v[36:39], v[0:15]
	v_exp_f32_e32 v208, v52
	v_exp_f32_e32 v209, v53
	v_exp_f32_e32 v210, v54
	v_exp_f32_e32 v211, v55
	v_cvt_pk_bf16_f32 v41, v206, v207
	v_cvt_pk_bf16_f32 v42, v208, v209
	v_cvt_pk_bf16_f32 v43, v210, v211
	v_exp_f32_e32 v212, v56
	v_exp_f32_e32 v213, v57
	v_mfma_f32_32x32x16_bf16 v[16:31], v[174:177], v[40:43], v[16:31]
	v_exp_f32_e32 v214, v58
	v_exp_f32_e32 v215, v59
	v_exp_f32_e32 v216, v60
	v_exp_f32_e32 v217, v61
	v_exp_f32_e32 v218, v62
	v_exp_f32_e32 v219, v63
	s_waitcnt lgkmcnt(13)
	v_mfma_f32_32x32x16_bf16 v[0:15], v[182:185], v[40:43], v[0:15]
	s_waitcnt lgkmcnt(12)
	s_mul_i32 s43, s59, 0x3400
	s_xor_b32 s44, s44, 1
	s_addk_i32 s9, 0x2000
	s_mov_b32 s59, s42
	s_mov_b32 s42, s22
	s_add_i32 s22, s43, 0
	s_mulk_i32 s44, 0x2400
	v_add_u32_e32 v221, s22, v160
	s_cmpk_lg_i32 s41, 0x7e
	v_add_u32_e32 v222, s22, v162
	v_add_u32_e32 v223, s22, v161
	v_add_u32_e32 v224, s44, v156
	s_waitcnt vmcnt(4)
	ds_write_b128 v221, v[140:143]
	s_waitcnt vmcnt(1)
	ds_write_b128 v223, v[148:151]
	ds_write_b128 v222, v[144:147]
	ds_write_b16 v224, v136 offset:39936
	ds_write_b16_d16_hi v224, v136 offset:40080
	ds_write_b16 v224, v137 offset:40224
	ds_write_b16_d16_hi v224, v137 offset:40368
	ds_write_b16 v224, v138 offset:40512
	ds_write_b16_d16_hi v224, v138 offset:40656
	ds_write_b16 v224, v139 offset:40800
	ds_write_b16_d16_hi v224, v139 offset:40944
	s_waitcnt vmcnt(0)
	ds_write_b16 v224, v132 offset:44544
	ds_write_b16_d16_hi v224, v132 offset:44688
	ds_write_b16 v224, v133 offset:44832
	ds_write_b16_d16_hi v224, v133 offset:44976
	ds_write_b16 v224, v134 offset:45120
	ds_write_b16_d16_hi v224, v134 offset:45264
	ds_write_b16 v224, v135 offset:45408
	ds_write_b16_d16_hi v224, v135 offset:45552
	v_cvt_pk_bf16_f32 v36, v212, v213
	v_cvt_pk_bf16_f32 v37, v214, v215
	v_cvt_pk_bf16_f32 v38, v216, v217
	v_cvt_pk_bf16_f32 v39, v218, v219
	s_nop 1
	v_mfma_f32_32x32x16_bf16 v[16:31], v[178:181], v[36:39], v[16:31]
	v_mfma_f32_32x32x16_bf16 v[0:15], v[186:189], v[36:39], v[0:15]
	s_waitcnt lgkmcnt(0)
	s_barrier
	s_cbranch_scc1 .LBB0_633
	s_add_i32 s8, s40, 0xfe000
	s_and_b32 s22, s8, 0xfe000
	v_lshl_add_u64 v[36:37], v[152:153], 0, s[22:23]
	global_load_dwordx4 v[132:135], v[36:37], off
	global_load_dwordx4 v[136:139], v[36:37], off offset:64
	s_setprio 1
	v_mfma_f32_32x32x16_bf16 v[48:63], v[32:35], v[84:87], 0
	v_add_f32_e32 v220, v163, v159
	v_add_f32_e32 v220, v204, v220
	v_add_f32_e32 v220, v173, v220
	v_mfma_f32_32x32x16_bf16 v[32:47], v[128:131], v[84:87], 0
	v_add_f32_e32 v220, v205, v220
	v_add_f32_e32 v220, v190, v220
	v_add_f32_e32 v220, v206, v220
	v_mfma_f32_32x32x16_bf16 v[32:47], v[124:127], v[80:83], v[32:47]
	v_add_f32_e32 v220, v191, v220
	v_add_f32_e32 v220, v207, v220
	v_add_f32_e32 v220, v192, v220
	v_mfma_f32_32x32x16_bf16 v[48:63], v[116:119], v[80:83], v[48:63]
	v_add_f32_e32 v220, v208, v220
	v_add_f32_e32 v220, v193, v220
	v_add_f32_e32 v220, v209, v220
	v_mfma_f32_32x32x16_bf16 v[32:47], v[108:111], v[76:79], v[32:47]
	v_add_f32_e32 v220, v194, v220
	v_add_f32_e32 v220, v210, v220
	v_add_f32_e32 v220, v195, v220
	v_mfma_f32_32x32x16_bf16 v[48:63], v[112:115], v[76:79], v[48:63]
	v_add_f32_e32 v220, v211, v220
	v_add_f32_e32 v220, v196, v220
	v_add_f32_e32 v220, v212, v220
	v_mfma_f32_32x32x16_bf16 v[32:47], v[104:107], v[72:75], v[32:47]
	v_add_f32_e32 v220, v197, v220
	v_add_f32_e32 v220, v213, v220
	v_add_f32_e32 v220, v198, v220
	v_mfma_f32_32x32x16_bf16 v[48:63], v[100:103], v[72:75], v[48:63]
	v_add_f32_e32 v220, v214, v220
	v_add_f32_e32 v220, v199, v220
	v_add_f32_e32 v220, v215, v220
	v_mfma_f32_32x32x16_bf16 v[32:47], v[120:123], v[68:71], v[32:47]
	v_add_f32_e32 v220, v200, v220
	v_add_f32_e32 v220, v216, v220
	v_mfma_f32_32x32x16_bf16 v[48:63], v[92:95], v[68:71], v[48:63]
	v_add_f32_e32 v220, v201, v220
	v_add_f32_e32 v220, v217, v220
	v_mfma_f32_32x32x16_bf16 v[32:47], v[96:99], v[64:67], v[32:47]
	v_add_f32_e32 v220, v202, v220
	v_add_f32_e32 v220, v218, v220
	v_mfma_f32_32x32x16_bf16 v[48:63], v[88:91], v[64:67], v[48:63]
	v_add_f32_e32 v220, v203, v220
	v_add_f32_e32 v159, v219, v220
	s_setprio 0
	ds_read_b128 v[88:91], v157 offset:39936
	ds_read_b128 v[92:95], v157 offset:39968
	ds_read_b128 v[96:99], v157 offset:44544
	ds_read_b128 v[100:103], v157 offset:44576
	ds_read_b128 v[104:107], v157 offset:40000
	ds_read_b128 v[108:111], v157 offset:40032
	ds_read_b128 v[112:115], v157 offset:44608
	ds_read_b128 v[116:119], v157 offset:44640
	s_nop 2
	v_exp_f32_e32 v140, v48
	v_exp_f32_e32 v141, v49
	v_exp_f32_e32 v142, v50
	v_exp_f32_e32 v143, v51
	v_exp_f32_e32 v52, v52
	v_exp_f32_e32 v53, v53
	v_exp_f32_e32 v54, v54
	v_exp_f32_e32 v55, v55
	v_cvt_pk_bf16_f32 v48, v140, v141
	v_cvt_pk_bf16_f32 v49, v142, v143
	v_cvt_pk_bf16_f32 v50, v52, v53
	v_cvt_pk_bf16_f32 v51, v54, v55
	v_exp_f32_e32 v56, v56
	v_exp_f32_e32 v57, v57
	s_waitcnt lgkmcnt(7)
	v_mfma_f32_32x32x16_bf16 v[16:31], v[88:91], v[48:51], v[16:31]
	v_exp_f32_e32 v58, v58
	v_exp_f32_e32 v59, v59
	v_exp_f32_e32 v60, v60
	v_exp_f32_e32 v61, v61
	v_exp_f32_e32 v62, v62
	v_exp_f32_e32 v63, v63
	v_exp_f32_e32 v144, v32
	s_waitcnt lgkmcnt(5)
	v_mfma_f32_32x32x16_bf16 v[0:15], v[96:99], v[48:51], v[0:15]
	v_cvt_pk_bf16_f32 v48, v56, v57
	v_cvt_pk_bf16_f32 v49, v58, v59
	v_cvt_pk_bf16_f32 v50, v60, v61
	v_cvt_pk_bf16_f32 v51, v62, v63
	v_exp_f32_e32 v145, v33
	v_exp_f32_e32 v146, v34
	v_exp_f32_e32 v147, v35
	v_mfma_f32_32x32x16_bf16 v[16:31], v[92:95], v[48:51], v[16:31]
	v_exp_f32_e32 v148, v36
	v_cvt_pk_bf16_f32 v32, v144, v145
	v_cvt_pk_bf16_f32 v33, v146, v147
	v_exp_f32_e32 v149, v41
	v_exp_f32_e32 v150, v42
	v_exp_f32_e32 v151, v43
	v_exp_f32_e32 v44, v44
	s_waitcnt lgkmcnt(4)
	v_mfma_f32_32x32x16_bf16 v[0:15], v[100:103], v[48:51], v[0:15]
	v_exp_f32_e32 v48, v37
	v_exp_f32_e32 v49, v38
	v_exp_f32_e32 v50, v39
	v_exp_f32_e32 v51, v40
	v_cvt_pk_bf16_f32 v34, v148, v48
	v_exp_f32_e32 v45, v45
	v_cvt_pk_bf16_f32 v35, v49, v50
	v_exp_f32_e32 v46, v46
	v_exp_f32_e32 v47, v47
	s_waitcnt lgkmcnt(3)
	v_mfma_f32_32x32x16_bf16 v[16:31], v[104:107], v[32:35], v[16:31]
	v_add_u32_e32 v128, s43, v158
	s_waitcnt lgkmcnt(1)
	v_mfma_f32_32x32x16_bf16 v[0:15], v[112:115], v[32:35], v[0:15]
	v_cvt_pk_bf16_f32 v32, v51, v149
	v_cvt_pk_bf16_f32 v33, v150, v151
	v_cvt_pk_bf16_f32 v34, v44, v45
	v_cvt_pk_bf16_f32 v35, v46, v47
	s_nop 1
	v_mfma_f32_32x32x16_bf16 v[16:31], v[108:111], v[32:35], v[16:31]
	ds_read_b128 v[36:39], v128
	ds_read_b128 v[88:91], v128 offset:32
	ds_read_b128 v[40:43], v128 offset:6656
	ds_read_b128 v[92:95], v128 offset:6688
	ds_read_b128 v[96:99], v128 offset:64
	ds_read_b128 v[100:103], v128 offset:96
	ds_read_b128 v[104:107], v128 offset:6720
	ds_read_b128 v[108:111], v128 offset:6752
	ds_read_b128 v[112:115], v128 offset:128
	ds_read_b128 v[120:123], v128 offset:160
	ds_read_b128 v[124:127], v128 offset:6784
	ds_read_b128 v[128:131], v128 offset:6816
	s_waitcnt lgkmcnt(12)
	v_mfma_f32_32x32x16_bf16 v[0:15], v[116:119], v[32:35], v[0:15]
	v_add_f32_e32 v32, v159, v140
	v_add_f32_e32 v32, v144, v32
	v_add_f32_e32 v32, v141, v32
	v_add_f32_e32 v32, v145, v32
	v_add_f32_e32 v32, v142, v32
	v_add_f32_e32 v32, v146, v32
	v_add_f32_e32 v32, v143, v32
	v_add_f32_e32 v32, v147, v32
	v_add_f32_e32 v32, v52, v32
	v_add_f32_e32 v32, v148, v32
	v_add_f32_e32 v32, v53, v32
	v_add_f32_e32 v32, v48, v32
	v_add_f32_e32 v32, v54, v32
	v_add_f32_e32 v32, v49, v32
	v_add_f32_e32 v32, v55, v32
	v_add_f32_e32 v32, v50, v32
	v_add_f32_e32 v32, v56, v32
	v_add_f32_e32 v32, v51, v32
	v_add_f32_e32 v32, v57, v32
	v_add_f32_e32 v32, v149, v32
	v_add_f32_e32 v32, v58, v32
	v_add_f32_e32 v32, v150, v32
	v_add_f32_e32 v32, v59, v32
	v_add_f32_e32 v32, v151, v32
	v_add_f32_e32 v32, v60, v32
	v_add_f32_e32 v32, v44, v32
	v_add_f32_e32 v32, v61, v32
	v_add_f32_e32 v32, v45, v32
	v_add_f32_e32 v32, v62, v32
	v_add_f32_e32 v32, v46, v32
	v_add_f32_e32 v32, v63, v32
	v_add_f32_e32 v116, v47, v32
	s_waitcnt vmcnt(1)
	ds_write_b16 v156, v132 offset:49152
	ds_write_b16_d16_hi v156, v132 offset:49296
	ds_write_b16 v156, v133 offset:49440
	ds_write_b16_d16_hi v156, v133 offset:49584
	ds_write_b16 v156, v134 offset:49728
	ds_write_b16_d16_hi v156, v134 offset:49872
	ds_write_b16 v156, v135 offset:50016
	ds_write_b16_d16_hi v156, v135 offset:50160
	s_waitcnt vmcnt(0)
	ds_write_b16 v156, v136 offset:53760
	ds_write_b16_d16_hi v156, v136 offset:53904
	ds_write_b16 v156, v137 offset:54048
	ds_write_b16_d16_hi v156, v137 offset:54192
	ds_write_b16 v156, v138 offset:54336
	ds_write_b16_d16_hi v156, v138 offset:54480
	ds_write_b16 v156, v139 offset:54624
	ds_write_b16_d16_hi v156, v139 offset:54768
	s_waitcnt lgkmcnt(0)
	s_barrier
	s_setprio 1
	v_mfma_f32_32x32x16_bf16 v[48:63], v[36:39], v[84:87], 0
	v_mfma_f32_32x32x16_bf16 v[32:47], v[40:43], v[84:87], 0
	v_mfma_f32_32x32x16_bf16 v[32:47], v[92:95], v[80:83], v[32:47]
	v_mfma_f32_32x32x16_bf16 v[48:63], v[88:91], v[80:83], v[48:63]
	v_mfma_f32_32x32x16_bf16 v[32:47], v[104:107], v[76:79], v[32:47]
	v_mfma_f32_32x32x16_bf16 v[48:63], v[96:99], v[76:79], v[48:63]
	v_mfma_f32_32x32x16_bf16 v[32:47], v[108:111], v[72:75], v[32:47]
	v_mfma_f32_32x32x16_bf16 v[48:63], v[100:103], v[72:75], v[48:63]
	v_mfma_f32_32x32x16_bf16 v[32:47], v[124:127], v[68:71], v[32:47]
	v_mfma_f32_32x32x16_bf16 v[48:63], v[112:115], v[68:71], v[48:63]
	v_mfma_f32_32x32x16_bf16 v[32:47], v[128:131], v[64:67], v[32:47]
	v_mfma_f32_32x32x16_bf16 v[48:63], v[120:123], v[64:67], v[48:63]
	s_setprio 0
	ds_read_b128 v[64:67], v157 offset:49152
	ds_read_b128 v[68:71], v157 offset:49184
	ds_read_b128 v[72:75], v157 offset:53760
	ds_read_b128 v[76:79], v157 offset:53792
	ds_read_b128 v[80:83], v157 offset:49216
	ds_read_b128 v[84:87], v157 offset:49248
	ds_read_b128 v[88:91], v157 offset:53824
	ds_read_b128 v[92:95], v157 offset:53856
	s_nop 2
	v_exp_f32_e32 v96, v48
	v_exp_f32_e32 v97, v49
	v_exp_f32_e32 v98, v50
	v_exp_f32_e32 v99, v51
	v_exp_f32_e32 v52, v52
	v_exp_f32_e32 v53, v53
	v_exp_f32_e32 v54, v54
	v_exp_f32_e32 v55, v55
	v_cvt_pk_bf16_f32 v48, v96, v97
	v_cvt_pk_bf16_f32 v49, v98, v99
	v_cvt_pk_bf16_f32 v50, v52, v53
	v_cvt_pk_bf16_f32 v51, v54, v55
	v_exp_f32_e32 v56, v56
	v_exp_f32_e32 v57, v57
	s_waitcnt lgkmcnt(7)
	v_mfma_f32_32x32x16_bf16 v[16:31], v[64:67], v[48:51], v[16:31]
	v_exp_f32_e32 v58, v58
	v_exp_f32_e32 v59, v59
	v_exp_f32_e32 v60, v60
	v_exp_f32_e32 v61, v61
	v_exp_f32_e32 v62, v62
	v_exp_f32_e32 v63, v63
	v_exp_f32_e32 v64, v32
	s_waitcnt lgkmcnt(5)
	v_mfma_f32_32x32x16_bf16 v[0:15], v[72:75], v[48:51], v[0:15]
	v_cvt_pk_bf16_f32 v48, v56, v57
	v_cvt_pk_bf16_f32 v49, v58, v59
	v_cvt_pk_bf16_f32 v50, v60, v61
	v_cvt_pk_bf16_f32 v51, v62, v63
	v_exp_f32_e32 v65, v33
	v_exp_f32_e32 v66, v34
	v_exp_f32_e32 v67, v35
	v_mfma_f32_32x32x16_bf16 v[16:31], v[68:71], v[48:51], v[16:31]
	v_exp_f32_e32 v36, v36
	v_exp_f32_e32 v37, v37
	v_exp_f32_e32 v38, v38
	v_exp_f32_e32 v39, v39
	v_cvt_pk_bf16_f32 v32, v64, v65
	v_cvt_pk_bf16_f32 v33, v66, v67
	v_cvt_pk_bf16_f32 v34, v36, v37
	s_waitcnt lgkmcnt(4)
	v_mfma_f32_32x32x16_bf16 v[0:15], v[76:79], v[48:51], v[0:15]
	v_cvt_pk_bf16_f32 v35, v38, v39
	v_add_f32_e32 v48, v116, v96
	v_add_f32_e32 v48, v64, v48
	v_exp_f32_e32 v40, v40
	v_exp_f32_e32 v41, v41
	v_exp_f32_e32 v42, v42
	v_exp_f32_e32 v43, v43
	s_waitcnt lgkmcnt(3)
	v_mfma_f32_32x32x16_bf16 v[16:31], v[80:83], v[32:35], v[16:31]
	v_exp_f32_e32 v44, v44
	v_exp_f32_e32 v45, v45
	v_exp_f32_e32 v46, v46
	v_exp_f32_e32 v47, v47
	v_add_f32_e32 v48, v97, v48
	v_add_f32_e32 v48, v65, v48
	v_add_f32_e32 v48, v98, v48
	s_waitcnt lgkmcnt(1)
	v_mfma_f32_32x32x16_bf16 v[0:15], v[88:91], v[32:35], v[0:15]
	v_add_f32_e32 v48, v66, v48
	v_cvt_pk_bf16_f32 v32, v40, v41
	v_cvt_pk_bf16_f32 v33, v42, v43
	v_cvt_pk_bf16_f32 v34, v44, v45
	v_cvt_pk_bf16_f32 v35, v46, v47
	v_add_f32_e32 v48, v99, v48
	s_waitcnt lgkmcnt(0)
	v_mfma_f32_32x32x16_bf16 v[16:31], v[84:87], v[32:35], v[16:31]
	s_barrier
	v_mfma_f32_32x32x16_bf16 v[0:15], v[92:95], v[32:35], v[0:15]
	v_add_f32_e32 v32, v67, v48
	v_add_f32_e32 v32, v52, v32
	v_add_f32_e32 v32, v36, v32
	v_add_f32_e32 v32, v53, v32
	v_add_f32_e32 v32, v37, v32
	v_add_f32_e32 v32, v54, v32
	v_add_f32_e32 v32, v38, v32
	v_add_f32_e32 v32, v55, v32
	v_add_f32_e32 v32, v39, v32
	v_add_f32_e32 v32, v56, v32
	v_add_f32_e32 v32, v40, v32
	v_add_f32_e32 v32, v57, v32
	v_add_f32_e32 v32, v41, v32
	v_add_f32_e32 v32, v58, v32
	v_add_f32_e32 v32, v42, v32
	v_add_f32_e32 v32, v59, v32
	v_add_f32_e32 v32, v43, v32
	v_add_f32_e32 v32, v60, v32
	v_add_f32_e32 v32, v44, v32
	v_add_f32_e32 v32, v61, v32
	v_add_f32_e32 v32, v45, v32
	v_add_f32_e32 v32, v62, v32
	v_add_f32_e32 v32, v46, v32
	v_add_f32_e32 v32, v63, v32
	v_add_f32_e32 v32, v47, v32
	v_mov_b32_e32 v33, v32
	s_nop 1
	v_permlane32_swap_b32_e32 v32, v33
	s_branch .LBB0_592
